# DMA-SPREAD: attention K/V rings of four slots, tile t+3 requested during tile t with its four LDS-DMA pieces spread between the MFMAs, counted vmcnt(4) at the tile barrier (on PEEL)
# speedup vs baseline: 1.0056x; 1.0056x over previous
.LBB0_985:
	s_and_b32 s42, s6, 7
	s_lshl_b32 s6, s26, 12
	s_and_b32 s27, s41, s40
	s_addk_i32 s6, 0x1000
	s_lshl_b32 s41, s26, 8
	s_and_b64 s[28:29], s[4:5], exec
	s_cselect_b32 s46, s6, s41
	s_lshr_b32 s45, s43, 2
	v_and_or_b32 v4, s45, 48, v152
	s_lshr_b32 s48, s43, 6
	v_lshl_add_u64 v[2:3], s[22:23], 0, v[130:131]
	s_lshl_b32 s6, s42, 8
	v_lshlrev_b32_e32 v4, 11, v4
	v_mov_b32_e32 v5, v131
	v_lshl_add_u64 v[2:3], v[2:3], 0, s[6:7]
	s_lshl_b32 s28, s48, 4
	s_mov_b32 s29, s7
	v_lshl_add_u64 v[4:5], s[24:25], 0, v[4:5]
	v_lshl_add_u64 v[2:3], v[2:3], 0, s[28:29]
	v_lshl_add_u64 v[4:5], v[4:5], 0, s[6:7]
	s_and_b32 s28, s45, 0x3fffffc0
	v_lshl_add_u64 v[4:5], v[4:5], 0, s[28:29]
	s_lshl_b32 s29, s48, 10
	v_mov_b32_e32 v139, v131
	s_add_i32 s48, s29, 0
	s_mov_b32 s49, m0
	s_mov_b32 m0, s48
	s_nop 0
	global_load_lds_dwordx4 v[2:3], off
	s_mov_b32 m0, s49
	v_lshl_add_u64 v[4:5], v[4:5], 0, v[138:139]
	v_lshl_add_u64 v[2:3], v[2:3], 0, s[16:17]
	s_add_i32 s49, s48, 0x2000
	s_mov_b32 s50, m0
	s_mov_b32 m0, s49
	s_nop 0
	global_load_lds_dwordx4 v[2:3], off
	s_mov_b32 m0, s50
	s_lshl_b32 s47, s27, 7
	s_lshr_b32 s27, s43, 7
	s_add_i32 s49, s48, 0x10000
	s_mov_b32 s50, m0
	s_mov_b32 m0, s49
	s_nop 0
	global_load_lds_dwordx4 v[4:5], off
	s_mov_b32 m0, s50
	v_lshl_add_u64 v[2:3], v[4:5], 0, s[16:17]
	s_add_i32 s48, s48, 0x12000
	s_mov_b32 s49, m0
	s_mov_b32 m0, s48
	s_nop 0
	global_load_lds_dwordx4 v[2:3], off
	s_mov_b32 m0, s49
	v_lshl_or_b32 v2, s27, 5, v151
	s_add_i32 s46, s46, s47
	v_add_u32_e32 v142, s46, v2
	v_ashrrev_i32_e32 v143, 31, v142
	v_lshlrev_b64 v[2:3], 11, v[142:143]
	s_bfe_u32 s41, s43, 0x10006
	v_lshl_add_u64 v[2:3], s[14:15], 0, v[2:3]
	v_lshl_add_u64 v[2:3], v[2:3], 0, s[6:7]
	s_lshl_b32 s46, s41, 7
	s_mov_b32 s47, s7
	v_lshl_add_u64 v[2:3], v[2:3], 0, s[46:47]
	v_mov_b32_e32 v141, v131
	v_lshl_add_u64 v[2:3], v[2:3], 0, v[140:141]
	global_load_dwordx4 v[126:129], v[2:3], off
	global_load_dwordx4 v[122:125], v[2:3], off offset:32
	global_load_dwordx4 v[118:121], v[2:3], off offset:64
	global_load_dwordx4 v[114:117], v[2:3], off offset:96
	s_andn2_b64 vcc, exec, s[4:5]
	s_waitcnt vmcnt(3)
	v_and_b32_e32 v2, 0xffff0000, v126
	v_lshlrev_b32_e32 v3, 16, v126
	v_mul_f32_e32 v2, v2, v2
	v_lshlrev_b32_e32 v4, 16, v127
	v_fmac_f32_e32 v2, v3, v3
	v_and_b32_e32 v5, 0xffff0000, v127
	v_fmac_f32_e32 v2, v4, v4
	v_lshlrev_b32_e32 v6, 16, v128
	v_fmac_f32_e32 v2, v5, v5
	v_and_b32_e32 v7, 0xffff0000, v128
	v_fmac_f32_e32 v2, v6, v6
	v_lshlrev_b32_e32 v8, 16, v129
	v_fmac_f32_e32 v2, v7, v7
	v_and_b32_e32 v9, 0xffff0000, v129
	v_fmac_f32_e32 v2, v8, v8
	s_waitcnt vmcnt(2)
	v_lshlrev_b32_e32 v10, 16, v122
	v_fmac_f32_e32 v2, v9, v9
	v_and_b32_e32 v11, 0xffff0000, v122
	v_fmac_f32_e32 v2, v10, v10
	v_lshlrev_b32_e32 v12, 16, v123
	v_fmac_f32_e32 v2, v11, v11
	v_and_b32_e32 v13, 0xffff0000, v123
	v_fmac_f32_e32 v2, v12, v12
	v_lshlrev_b32_e32 v14, 16, v124
	v_fmac_f32_e32 v2, v13, v13
	v_and_b32_e32 v15, 0xffff0000, v124
	v_fmac_f32_e32 v2, v14, v14
	v_lshlrev_b32_e32 v16, 16, v125
	v_fmac_f32_e32 v2, v15, v15
	v_and_b32_e32 v17, 0xffff0000, v125
	v_fmac_f32_e32 v2, v16, v16
	s_waitcnt vmcnt(1)
	v_lshlrev_b32_e32 v18, 16, v118
	v_fmac_f32_e32 v2, v17, v17
	v_and_b32_e32 v19, 0xffff0000, v118
	v_fmac_f32_e32 v2, v18, v18
	v_lshlrev_b32_e32 v20, 16, v119
	v_fmac_f32_e32 v2, v19, v19
	v_and_b32_e32 v21, 0xffff0000, v119
	v_fmac_f32_e32 v2, v20, v20
	v_lshlrev_b32_e32 v22, 16, v120
	v_fmac_f32_e32 v2, v21, v21
	v_and_b32_e32 v23, 0xffff0000, v120
	v_fmac_f32_e32 v2, v22, v22
	v_lshlrev_b32_e32 v24, 16, v121
	v_fmac_f32_e32 v2, v23, v23
	v_and_b32_e32 v25, 0xffff0000, v121
	v_fmac_f32_e32 v2, v24, v24
	s_waitcnt vmcnt(0)
	v_lshlrev_b32_e32 v26, 16, v114
	v_fmac_f32_e32 v2, v25, v25
	v_and_b32_e32 v27, 0xffff0000, v114
	v_fmac_f32_e32 v2, v26, v26
	v_lshlrev_b32_e32 v28, 16, v115
	v_fmac_f32_e32 v2, v27, v27
	v_and_b32_e32 v29, 0xffff0000, v115
	v_fmac_f32_e32 v2, v28, v28
	v_lshlrev_b32_e32 v30, 16, v116
	v_fmac_f32_e32 v2, v29, v29
	v_and_b32_e32 v31, 0xffff0000, v116
	v_fmac_f32_e32 v2, v30, v30
	v_lshlrev_b32_e32 v32, 16, v117
	v_fmac_f32_e32 v2, v31, v31
	v_fmac_f32_e32 v2, v32, v32
	v_and_b32_e32 v3, 0xffff0000, v117
	v_fmac_f32_e32 v2, v3, v3
	ds_bpermute_b32 v3, v1, v2
	v_mov_b32_e32 v4, v149
	s_cbranch_vccnz .LBB0_987
	s_lshl_b32 s4, s26, 4
	s_lshl_b32 s5, s42, 1
	s_or_b32 s4, s4, s5
	s_or_b32 s4, s4, s41
	s_ashr_i32 s5, s4, 31
	s_lshl_b64 s[4:5], s[4:5], 2
	s_add_u32 s4, s33, s4
	s_addc_u32 s5, s34, s5
	global_load_dword v4, v131, s[4:5]
	s_waitcnt vmcnt(0)
	v_mul_f32_e32 v5, 0x4f800000, v4
	v_cmp_gt_f32_e32 vcc, s36, v4
	s_nop 1
	v_cndmask_b32_e32 v4, v4, v5, vcc
	v_sqrt_f32_e32 v5, v4
	s_nop 0
	v_add_u32_e32 v6, -1, v5
	v_add_u32_e32 v7, 1, v5
	v_fma_f32 v8, -v6, v5, v4
	v_fma_f32 v9, -v7, v5, v4
	v_cmp_ge_f32_e64 s[4:5], 0, v8
	s_nop 1
	v_cndmask_b32_e64 v5, v5, v6, s[4:5]
	v_cmp_lt_f32_e64 s[4:5], 0, v9
	s_nop 1
	v_cndmask_b32_e64 v5, v5, v7, s[4:5]
	v_mul_f32_e32 v6, 0x37800000, v5
	v_cndmask_b32_e32 v5, v5, v6, vcc
	v_cmp_class_f32_e32 vcc, v4, v156
	s_nop 1
	v_cndmask_b32_e32 v4, v5, v4, vcc
	v_mul_f32_e32 v4, 0x3f8147ae, v4
	v_max_f32_e32 v5, v149, v149
	v_max_f32_e32 v4, v5, v4
.LBB0_987:
	s_waitcnt lgkmcnt(0)
	v_add_f32_e32 v2, v2, v3
	v_mul_f32_e32 v3, 0x4f800000, v2
	v_cmp_gt_f32_e32 vcc, s36, v2
	s_lshl_b32 s26, s42, 7
	s_add_i32 s42, s29, 0x2000
	v_cndmask_b32_e32 v2, v2, v3, vcc
	v_sqrt_f32_e32 v3, v2
	v_mov_b32_e32 v139, 0
	v_lshl_add_u32 v141, s41, 13, v154
	v_mov_b32_e32 v7, v139
	v_add_u32_e32 v5, -1, v3
	v_fma_f32 v6, -v5, v3, v2
	v_cmp_ge_f32_e64 s[4:5], 0, v6
	v_add_u32_e32 v6, 1, v3
	v_mov_b32_e32 v8, v139
	v_cndmask_b32_e64 v5, v3, v5, s[4:5]
	v_fma_f32 v3, -v6, v3, v2
	v_cmp_lt_f32_e64 s[4:5], 0, v3
	v_mov_b32_e32 v9, v139
	v_mov_b32_e32 v10, v139
	v_cndmask_b32_e64 v3, v5, v6, s[4:5]
	v_mul_f32_e32 v5, 0x37800000, v3
	v_cndmask_b32_e32 v3, v3, v5, vcc
	v_cmp_class_f32_e32 vcc, v2, v156
	s_add_i32 s4, s44, 1
	s_and_b32 s5, s45, 0x3ffffff0
	v_cndmask_b32_e32 v2, v3, v2, vcc
	v_mul_f32_e64 v66, v2, -v4
	v_lshl_add_u64 v[2:3], s[22:23], 0, v[134:135]
	s_add_u32 s22, s6, s5
	s_addc_u32 s23, 0, 0
	v_lshl_add_u64 v[144:145], v[2:3], 0, s[22:23]
	s_add_u32 s22, s6, s28
	s_addc_u32 s23, 0, 0
	s_lshl_b32 s5, s43, 9
	s_and_b32 s5, s5, 0x18000
	v_lshl_or_b32 v4, v155, 1, s5
	v_mov_b32_e32 v5, v131
	v_lshl_add_u64 v[2:3], s[24:25], 0, v[136:137]
	v_lshl_add_u64 v[4:5], s[22:23], 0, v[4:5]
	v_mov_b32_e32 v67, v66
	v_mov_b32_e32 v68, v66
	v_mov_b32_e32 v69, v66
	v_mov_b32_e32 v70, v66
	v_mov_b32_e32 v71, v66
	v_mov_b32_e32 v72, v66
	v_mov_b32_e32 v73, v66
	v_mov_b32_e32 v74, v66
	v_mov_b32_e32 v75, v66
	v_mov_b32_e32 v76, v66
	v_mov_b32_e32 v77, v66
	v_mov_b32_e32 v78, v66
	v_mov_b32_e32 v79, v66
	v_mov_b32_e32 v80, v66
	v_mov_b32_e32 v81, v66
	v_lshl_add_u64 v[146:147], v[2:3], 0, v[4:5]
	s_mov_b32 s6, 0
	v_mov_b32_e32 v2, 0
	v_mov_b32_e32 v3, v139
	v_mov_b32_e32 v4, v139
	v_mov_b32_e32 v5, v139
	v_mov_b32_e32 v6, v139
	v_mov_b32_e32 v11, v139
	v_mov_b32_e32 v12, v139
	v_mov_b32_e32 v13, v139
	v_mov_b32_e32 v14, v139
	v_mov_b32_e32 v15, v139
	v_mov_b32_e32 v16, v139
	v_mov_b32_e32 v17, v139
	v_mov_b32_e32 v18, 0
	v_mov_b32_e32 v19, v139
	v_mov_b32_e32 v20, v139
	v_mov_b32_e32 v21, v139
	v_mov_b32_e32 v22, v139
	v_mov_b32_e32 v23, v139
	v_mov_b32_e32 v24, v139
	v_mov_b32_e32 v25, v139
	v_mov_b32_e32 v26, v139
	v_mov_b32_e32 v27, v139
	v_mov_b32_e32 v28, v139
	v_mov_b32_e32 v29, v139
	v_mov_b32_e32 v30, v139
	v_mov_b32_e32 v31, v139
	v_mov_b32_e32 v32, v139
	v_mov_b32_e32 v33, v139
	v_mov_b32_e32 v34, 0
	v_mov_b32_e32 v35, v139
	v_mov_b32_e32 v36, v139
	v_mov_b32_e32 v37, v139
	v_mov_b32_e32 v38, v139
	v_mov_b32_e32 v39, v139
	v_mov_b32_e32 v40, v139
	v_mov_b32_e32 v41, v139
	v_mov_b32_e32 v42, v139
	v_mov_b32_e32 v43, v139
	v_mov_b32_e32 v44, v139
	v_mov_b32_e32 v45, v139
	v_mov_b32_e32 v46, v139
	v_mov_b32_e32 v47, v139
	v_mov_b32_e32 v48, v139
	v_mov_b32_e32 v49, v139
	v_mov_b32_e32 v50, 0
	v_mov_b32_e32 v51, v139
	v_mov_b32_e32 v52, v139
	v_mov_b32_e32 v53, v139
	v_mov_b32_e32 v54, v139
	v_mov_b32_e32 v55, v139
	v_mov_b32_e32 v56, v139
	v_mov_b32_e32 v57, v139
	v_mov_b32_e32 v58, v139
	v_mov_b32_e32 v59, v139
	v_mov_b32_e32 v60, v139
	v_mov_b32_e32 v61, v139
	v_mov_b32_e32 v62, v139
	v_mov_b32_e32 v63, v139
	v_mov_b32_e32 v64, v139
	v_mov_b32_e32 v65, v139
	s_movk_i32 s23, 0x4000
	s_mov_b32 s28, m0
	s_add_i32 s24, s23, s29
	s_mov_b32 m0, s24
	s_add_i32 s25, s23, s42
	global_load_lds_dwordx4 v[144:145], off
	s_addk_i32 s25, 0xff80
	s_mov_b32 m0, s25
	s_add_i32 s24, s24, 0x10000
	global_load_lds_dwordx4 v[144:145], off offset:128
	s_mov_b32 m0, s24
	s_add_i32 s25, s25, 0x10000
	global_load_lds_dwordx4 v[146:147], off
	s_mov_b32 m0, s25
	v_lshl_add_u64 v[144:145], v[144:145], 0, s[18:19]
	global_load_lds_dwordx4 v[146:147], off offset:128
	s_mov_b32 m0, s28
	v_lshl_add_u64 v[146:147], v[146:147], 0, s[18:19]
	s_mov_b32 s23, 0x8000
	s_mov_b32 s28, m0
	s_add_i32 s24, s23, s29
	s_mov_b32 m0, s24
	s_add_i32 s25, s23, s42
	global_load_lds_dwordx4 v[144:145], off
	s_addk_i32 s25, 0xff80
	s_mov_b32 m0, s25
	s_add_i32 s24, s24, 0x10000
	global_load_lds_dwordx4 v[144:145], off offset:128
	s_mov_b32 m0, s24
	s_add_i32 s25, s25, 0x10000
	global_load_lds_dwordx4 v[146:147], off
	s_mov_b32 m0, s25
	v_lshl_add_u64 v[144:145], v[144:145], 0, s[18:19]
	global_load_lds_dwordx4 v[146:147], off offset:128
	s_mov_b32 m0, s28
	v_lshl_add_u64 v[146:147], v[146:147], 0, s[18:19]
	s_waitcnt vmcnt(8) lgkmcnt(0)
	s_barrier
	v_mov_b32_e32 v159, v141
	ds_read_b128 v[210:213], v159
	ds_read_b128 v[214:217], v159 offset:512
	ds_read_b128 v[218:221], v159 offset:2048
	ds_read_b128 v[222:225], v159 offset:2560
	ds_read_b128 v[226:229], v159 offset:4096
	ds_read_b128 v[230:233], v159 offset:4608
	ds_read_b128 v[234:237], v159 offset:6144
	ds_read_b128 v[238:241], v159 offset:6656
	s_waitcnt lgkmcnt(7)
	v_mfma_f32_32x32x16_bf16 v[98:113], v[210:213], v[126:129], v[66:81]
	s_waitcnt lgkmcnt(5)
	v_mfma_f32_32x32x16_bf16 v[98:113], v[218:221], v[122:125], v[98:113]
	s_waitcnt lgkmcnt(3)
	v_mfma_f32_32x32x16_bf16 v[98:113], v[226:229], v[118:121], v[98:113]
	s_waitcnt lgkmcnt(1)
	v_mfma_f32_32x32x16_bf16 v[98:113], v[234:237], v[114:117], v[98:113]
	v_mfma_f32_32x32x16_bf16 v[82:97], v[214:217], v[126:129], v[66:81]
	v_mfma_f32_32x32x16_bf16 v[82:97], v[222:225], v[122:125], v[82:97]
	v_mfma_f32_32x32x16_bf16 v[82:97], v[230:233], v[118:121], v[82:97]
	s_waitcnt lgkmcnt(0)
	v_mfma_f32_32x32x16_bf16 v[82:97], v[238:241], v[114:117], v[82:97]
	s_nop 6
	v_exp_f32_e32 v98, v98
	v_exp_f32_e32 v99, v99
	v_exp_f32_e32 v100, v100
	v_exp_f32_e32 v101, v101
	v_exp_f32_e32 v102, v102
	v_exp_f32_e32 v103, v103
	v_exp_f32_e32 v104, v104
	v_exp_f32_e32 v105, v105
	v_exp_f32_e32 v106, v106
	v_exp_f32_e32 v107, v107
	v_exp_f32_e32 v108, v108
	v_exp_f32_e32 v109, v109
	v_exp_f32_e32 v110, v110
	v_exp_f32_e32 v111, v111
	v_exp_f32_e32 v112, v112
	v_exp_f32_e32 v113, v113
	v_exp_f32_e32 v82, v82
	v_exp_f32_e32 v83, v83
	v_exp_f32_e32 v84, v84
	v_exp_f32_e32 v85, v85
	v_exp_f32_e32 v86, v86
	v_exp_f32_e32 v87, v87
	v_exp_f32_e32 v88, v88
	v_exp_f32_e32 v89, v89
	v_exp_f32_e32 v90, v90
	v_exp_f32_e32 v91, v91
	v_exp_f32_e32 v92, v92
	v_exp_f32_e32 v93, v93
	v_exp_f32_e32 v94, v94
	v_exp_f32_e32 v95, v95
	v_exp_f32_e32 v96, v96
	v_exp_f32_e32 v97, v97
	v_cvt_pk_bf16_f32 v194, v98, v99
	v_cvt_pk_bf16_f32 v195, v100, v101
	v_cvt_pk_bf16_f32 v196, v102, v103
	v_cvt_pk_bf16_f32 v197, v104, v105
	v_cvt_pk_bf16_f32 v198, v106, v107
	v_cvt_pk_bf16_f32 v199, v108, v109
	v_cvt_pk_bf16_f32 v200, v110, v111
	v_cvt_pk_bf16_f32 v201, v112, v113
	v_cvt_pk_bf16_f32 v202, v82, v83
	v_cvt_pk_bf16_f32 v203, v84, v85
	v_cvt_pk_bf16_f32 v204, v86, v87
	v_cvt_pk_bf16_f32 v205, v88, v89
	v_cvt_pk_bf16_f32 v206, v90, v91
	v_cvt_pk_bf16_f32 v207, v92, v93
	v_cvt_pk_bf16_f32 v208, v94, v95
	v_cvt_pk_bf16_f32 v209, v96, v97
	s_mov_b32 s6, 0
	s_mov_b32 s28, m0
.Lat3_loop:
	s_add_i32 s22, s6, 1
	s_and_b32 s22, s22, 3
	s_add_i32 s23, s6, 2
	s_and_b32 s23, s23, 3
	s_add_i32 s78, s6, 3
	s_and_b32 s78, s78, 3
	s_lshl_b32 s24, s6, 14
	s_lshl_b32 s25, s22, 14
	s_lshl_b32 s23, s23, 14
	s_lshl_b32 s78, s78, 14
	s_add_i32 s24, s24, 0x4000
	v_add_u32_e32 v248, s24, v153
	v_add_u32_e32 v159, s25, v141
	ds_read_b64_tr_b16 v[168:169], v248 offset:49152
	ds_read_b64_tr_b16 v[170:171], v248 offset:49664
	ds_read_b64_tr_b16 v[172:173], v248 offset:53248
	ds_read_b64_tr_b16 v[174:175], v248 offset:53760
	ds_read_b64_tr_b16 v[176:177], v248 offset:57344
	ds_read_b64_tr_b16 v[178:179], v248 offset:57856
	ds_read_b64_tr_b16 v[180:181], v248 offset:61440
	ds_read_b64_tr_b16 v[182:183], v248 offset:61952
	s_cmp_gt_u32 s4, 2
	s_cselect_b32 s79, 1, 0
	s_cmp_lt_u32 s4, 2
	s_cbranch_scc1 .Lat3_w0
	s_waitcnt vmcnt(4)
	s_branch .Lat3_w1

.Lat3_w1:
	s_barrier
	ds_read_b128 v[210:213], v159
	ds_read_b128 v[218:221], v159 offset:2048
	ds_read_b128 v[226:229], v159 offset:4096
	ds_read_b128 v[234:237], v159 offset:6144
	s_cmp_eq_u32 s79, 0
	s_cbranch_scc1 .Lat3_np0
	s_add_i32 s24, s78, s29
	s_mov_b32 m0, s24
	s_nop 0
	global_load_lds_dwordx4 v[144:145], off
.Lat3_np0:
	s_waitcnt lgkmcnt(8)
	v_mfma_f32_32x32x16_bf16 v[50:65], v[168:171], v[194:197], v[50:65]
	ds_read_b128 v[214:217], v159 offset:512
	ds_read_b128 v[222:225], v159 offset:2560
	v_add_f32_e32 v246, 0, v98
	v_add_f32_e32 v246, v99, v246
	v_add_f32_e32 v246, v100, v246
	v_add_f32_e32 v246, v101, v246
	v_add_f32_e32 v247, 0, v82
	v_add_f32_e32 v247, v83, v247
	v_mfma_f32_32x32x16_bf16 v[34:49], v[172:175], v[194:197], v[34:49]
	ds_read_b128 v[230:233], v159 offset:4608
	ds_read_b128 v[238:241], v159 offset:6656
	v_add_f32_e32 v246, v102, v246
	v_add_f32_e32 v246, v103, v246
	v_add_f32_e32 v246, v104, v246
	v_add_f32_e32 v246, v105, v246
	v_add_f32_e32 v247, v84, v247
	v_add_f32_e32 v247, v85, v247
	s_cmp_eq_u32 s79, 0
	s_cbranch_scc1 .Lat3_np1
	s_add_i32 s25, s78, s42
	s_addk_i32 s25, 0xff80
	s_mov_b32 m0, s25
	s_nop 0
	global_load_lds_dwordx4 v[144:145], off offset:128
	v_lshl_add_u64 v[144:145], v[144:145], 0, s[18:19]
.Lat3_np1:
	s_waitcnt lgkmcnt(8)
	v_mfma_f32_32x32x16_bf16 v[18:33], v[176:179], v[194:197], v[18:33]
	v_add_f32_e32 v246, v106, v246
	v_add_f32_e32 v246, v107, v246
	v_add_f32_e32 v246, v108, v246
	v_add_f32_e32 v246, v109, v246
	v_add_f32_e32 v247, v86, v247
	v_add_f32_e32 v247, v87, v247
	v_mfma_f32_32x32x16_bf16 v[2:17], v[180:183], v[194:197], v[2:17]
	v_add_f32_e32 v246, v110, v246
	v_add_f32_e32 v246, v111, v246
	v_add_f32_e32 v246, v112, v246
	v_add_f32_e32 v246, v113, v246
	v_add_f32_e32 v247, v88, v247
	v_add_f32_e32 v247, v89, v247
	v_add_f32_e32 v246, v139, v246
	s_cmp_eq_u32 s79, 0
	s_cbranch_scc1 .Lat3_np2
	s_add_i32 s24, s78, s29
	s_add_i32 s24, s24, 0x10000
	s_mov_b32 m0, s24
	s_nop 0
	global_load_lds_dwordx4 v[146:147], off
.Lat3_np2:
	ds_read_b64_tr_b16 v[184:185], v248 offset:50176
	ds_read_b64_tr_b16 v[186:187], v248 offset:50688
	ds_read_b64_tr_b16 v[188:189], v248 offset:54272
	ds_read_b64_tr_b16 v[190:191], v248 offset:54784
	s_waitcnt lgkmcnt(10)
	v_mfma_f32_32x32x16_bf16 v[98:113], v[210:213], v[126:129], v[66:81]
	v_add_f32_e32 v247, v90, v247
	v_add_f32_e32 v247, v91, v247
	v_mfma_f32_32x32x16_bf16 v[98:113], v[218:221], v[122:125], v[98:113]
	v_add_f32_e32 v247, v92, v247
	v_add_f32_e32 v247, v93, v247
	s_cmp_eq_u32 s79, 0
	s_cbranch_scc1 .Lat3_np3
	s_add_i32 s25, s78, s42
	s_add_i32 s25, s25, 0xff80
	s_mov_b32 m0, s25
	s_nop 0
	global_load_lds_dwordx4 v[146:147], off offset:128
	v_lshl_add_u64 v[146:147], v[146:147], 0, s[18:19]
.Lat3_np3:
	s_waitcnt lgkmcnt(8)
	v_mfma_f32_32x32x16_bf16 v[98:113], v[226:229], v[118:121], v[98:113]
	v_add_f32_e32 v247, v94, v247
	v_add_f32_e32 v247, v95, v247
	v_mfma_f32_32x32x16_bf16 v[98:113], v[234:237], v[114:117], v[98:113]
	v_add_f32_e32 v247, v96, v247
	v_add_f32_e32 v247, v97, v247
	v_add_f32_e32 v139, v246, v247
	ds_read_b64_tr_b16 v[160:161], v248 offset:58368
	ds_read_b64_tr_b16 v[162:163], v248 offset:58880
	ds_read_b64_tr_b16 v[242:243], v248 offset:62464
	ds_read_b64_tr_b16 v[244:245], v248 offset:62976
	s_waitcnt lgkmcnt(4)
	v_mfma_f32_32x32x16_bf16 v[50:65], v[184:187], v[198:201], v[50:65]
	v_mfma_f32_32x32x16_bf16 v[34:49], v[188:191], v[198:201], v[34:49]
	ds_read_b64_tr_b16 v[168:169], v248 offset:51200
	ds_read_b64_tr_b16 v[170:171], v248 offset:51712
	ds_read_b64_tr_b16 v[172:173], v248 offset:55296
	ds_read_b64_tr_b16 v[174:175], v248 offset:55808
	s_waitcnt lgkmcnt(4)
	v_mfma_f32_32x32x16_bf16 v[18:33], v[160:163], v[198:201], v[18:33]
	v_exp_f32_e32 v98, v98
	v_exp_f32_e32 v99, v99
	v_exp_f32_e32 v100, v100
	v_mfma_f32_32x32x16_bf16 v[2:17], v[242:245], v[198:201], v[2:17]
	ds_read_b64_tr_b16 v[176:177], v248 offset:59392
	ds_read_b64_tr_b16 v[178:179], v248 offset:59904
	ds_read_b64_tr_b16 v[180:181], v248 offset:63488
	ds_read_b64_tr_b16 v[182:183], v248 offset:64000
	v_exp_f32_e32 v101, v101
	v_exp_f32_e32 v102, v102
	v_mfma_f32_32x32x16_bf16 v[82:97], v[214:217], v[126:129], v[66:81]
	ds_read_b64_tr_b16 v[184:185], v248 offset:52224
	ds_read_b64_tr_b16 v[186:187], v248 offset:52736
	ds_read_b64_tr_b16 v[188:189], v248 offset:56320
	ds_read_b64_tr_b16 v[190:191], v248 offset:56832
	v_exp_f32_e32 v103, v103
	v_exp_f32_e32 v104, v104
	v_mfma_f32_32x32x16_bf16 v[82:97], v[222:225], v[122:125], v[82:97]
	v_exp_f32_e32 v105, v105
	v_exp_f32_e32 v106, v106
	v_exp_f32_e32 v107, v107
	v_mfma_f32_32x32x16_bf16 v[82:97], v[230:233], v[118:121], v[82:97]
	v_exp_f32_e32 v108, v108
	v_exp_f32_e32 v109, v109
	v_exp_f32_e32 v110, v110
	v_mfma_f32_32x32x16_bf16 v[82:97], v[238:241], v[114:117], v[82:97]
	v_exp_f32_e32 v111, v111
	v_exp_f32_e32 v112, v112
	v_exp_f32_e32 v113, v113
	s_waitcnt lgkmcnt(8)
	v_mfma_f32_32x32x16_bf16 v[50:65], v[168:171], v[202:205], v[50:65]
	v_cvt_pk_bf16_f32 v194, v98, v99
	v_cvt_pk_bf16_f32 v195, v100, v101
	v_cvt_pk_bf16_f32 v196, v102, v103
	v_cvt_pk_bf16_f32 v197, v104, v105
	v_mfma_f32_32x32x16_bf16 v[34:49], v[172:175], v[202:205], v[34:49]
	ds_read_b64_tr_b16 v[160:161], v248 offset:60416
	ds_read_b64_tr_b16 v[162:163], v248 offset:60928
	ds_read_b64_tr_b16 v[242:243], v248 offset:64512
	ds_read_b64_tr_b16 v[244:245], v248 offset:65024
	v_cvt_pk_bf16_f32 v198, v106, v107
	v_cvt_pk_bf16_f32 v199, v108, v109
	v_cvt_pk_bf16_f32 v200, v110, v111
	v_cvt_pk_bf16_f32 v201, v112, v113
	s_waitcnt lgkmcnt(8)
	v_mfma_f32_32x32x16_bf16 v[18:33], v[176:179], v[202:205], v[18:33]
	v_exp_f32_e32 v82, v82
	v_exp_f32_e32 v83, v83
	v_exp_f32_e32 v84, v84
	v_mfma_f32_32x32x16_bf16 v[2:17], v[180:183], v[202:205], v[2:17]
	v_exp_f32_e32 v85, v85
	v_exp_f32_e32 v86, v86
	v_exp_f32_e32 v87, v87
	s_waitcnt lgkmcnt(4)
	v_mfma_f32_32x32x16_bf16 v[50:65], v[184:187], v[206:209], v[50:65]
	v_exp_f32_e32 v88, v88
	v_exp_f32_e32 v89, v89
	v_exp_f32_e32 v90, v90
	v_mfma_f32_32x32x16_bf16 v[34:49], v[188:191], v[206:209], v[34:49]
	v_exp_f32_e32 v91, v91
	v_exp_f32_e32 v92, v92
	v_exp_f32_e32 v93, v93
	s_waitcnt lgkmcnt(0)
	v_mfma_f32_32x32x16_bf16 v[18:33], v[160:163], v[206:209], v[18:33]
	v_exp_f32_e32 v94, v94
	v_exp_f32_e32 v95, v95
	v_exp_f32_e32 v96, v96
	v_mfma_f32_32x32x16_bf16 v[2:17], v[242:245], v[206:209], v[2:17]
	v_exp_f32_e32 v97, v97
	v_cvt_pk_bf16_f32 v202, v82, v83
	v_cvt_pk_bf16_f32 v203, v84, v85
	v_cvt_pk_bf16_f32 v204, v86, v87
	v_cvt_pk_bf16_f32 v205, v88, v89
	v_cvt_pk_bf16_f32 v206, v90, v91
	v_cvt_pk_bf16_f32 v207, v92, v93
	v_cvt_pk_bf16_f32 v208, v94, v95
	v_cvt_pk_bf16_f32 v209, v96, v97
	s_add_i32 s4, s4, -1
	s_mov_b32 s6, s22
	s_cmp_eq_u32 s4, 0
	s_cbranch_scc0 .Lat3_loop
	s_mov_b32 m0, s28
	s_lshl_b32 s24, s6, 14
	s_add_i32 s24, s24, 0x4000
	v_add_u32_e32 v248, s24, v153
	ds_read_b64_tr_b16 v[168:169], v248 offset:49152
	ds_read_b64_tr_b16 v[170:171], v248 offset:49664
	ds_read_b64_tr_b16 v[172:173], v248 offset:53248
	ds_read_b64_tr_b16 v[174:175], v248 offset:53760
	ds_read_b64_tr_b16 v[176:177], v248 offset:57344
	ds_read_b64_tr_b16 v[178:179], v248 offset:57856
	ds_read_b64_tr_b16 v[180:181], v248 offset:61440
	ds_read_b64_tr_b16 v[182:183], v248 offset:61952
	s_waitcnt lgkmcnt(6)
	v_mfma_f32_32x32x16_bf16 v[50:65], v[168:171], v[194:197], v[50:65]
	v_add_f32_e32 v246, 0, v98
	v_add_f32_e32 v247, 0, v82
	v_add_f32_e32 v246, v99, v246
	v_add_f32_e32 v247, v83, v247
	s_waitcnt lgkmcnt(4)
	v_mfma_f32_32x32x16_bf16 v[34:49], v[172:175], v[194:197], v[34:49]
	ds_read_b64_tr_b16 v[184:185], v248 offset:50176
	ds_read_b64_tr_b16 v[186:187], v248 offset:50688
	ds_read_b64_tr_b16 v[188:189], v248 offset:54272
	ds_read_b64_tr_b16 v[190:191], v248 offset:54784
	v_add_f32_e32 v246, v100, v246
	v_add_f32_e32 v247, v84, v247
	v_add_f32_e32 v246, v101, v246
	v_add_f32_e32 v247, v85, v247
	s_waitcnt lgkmcnt(6)
	v_mfma_f32_32x32x16_bf16 v[18:33], v[176:179], v[194:197], v[18:33]
	v_add_f32_e32 v246, v102, v246
	v_add_f32_e32 v247, v86, v247
	v_add_f32_e32 v246, v103, v246
	v_add_f32_e32 v247, v87, v247
	s_waitcnt lgkmcnt(4)
	v_mfma_f32_32x32x16_bf16 v[2:17], v[180:183], v[194:197], v[2:17]
	ds_read_b64_tr_b16 v[160:161], v248 offset:58368
	ds_read_b64_tr_b16 v[162:163], v248 offset:58880
	ds_read_b64_tr_b16 v[242:243], v248 offset:62464
	ds_read_b64_tr_b16 v[244:245], v248 offset:62976
	v_add_f32_e32 v246, v104, v246
	v_add_f32_e32 v247, v88, v247
	v_add_f32_e32 v246, v105, v246
	v_add_f32_e32 v247, v89, v247
	s_waitcnt lgkmcnt(6)
	v_mfma_f32_32x32x16_bf16 v[50:65], v[184:187], v[198:201], v[50:65]
	v_add_f32_e32 v246, v106, v246
	v_add_f32_e32 v247, v90, v247
	v_add_f32_e32 v246, v107, v246
	v_add_f32_e32 v247, v91, v247
	s_waitcnt lgkmcnt(4)
	v_mfma_f32_32x32x16_bf16 v[34:49], v[188:191], v[198:201], v[34:49]
	ds_read_b64_tr_b16 v[168:169], v248 offset:51200
	ds_read_b64_tr_b16 v[170:171], v248 offset:51712
	ds_read_b64_tr_b16 v[172:173], v248 offset:55296
	ds_read_b64_tr_b16 v[174:175], v248 offset:55808
	v_add_f32_e32 v246, v108, v246
	v_add_f32_e32 v247, v92, v247
	v_add_f32_e32 v246, v109, v246
	v_add_f32_e32 v247, v93, v247
	s_waitcnt lgkmcnt(6)
	v_mfma_f32_32x32x16_bf16 v[18:33], v[160:163], v[198:201], v[18:33]
	v_add_f32_e32 v246, v110, v246
	v_add_f32_e32 v247, v94, v247
	v_add_f32_e32 v246, v111, v246
	v_add_f32_e32 v247, v95, v247
	s_waitcnt lgkmcnt(4)
	v_mfma_f32_32x32x16_bf16 v[2:17], v[242:245], v[198:201], v[2:17]
	ds_read_b64_tr_b16 v[176:177], v248 offset:59392
	ds_read_b64_tr_b16 v[178:179], v248 offset:59904
	ds_read_b64_tr_b16 v[180:181], v248 offset:63488
	ds_read_b64_tr_b16 v[182:183], v248 offset:64000
	v_add_f32_e32 v246, v112, v246
	v_add_f32_e32 v247, v96, v247
	v_add_f32_e32 v246, v113, v246
	v_add_f32_e32 v247, v97, v247
	v_add_f32_e32 v246, v139, v246
	v_add_f32_e32 v139, v246, v247
	v_mov_b32_e32 v90, v139
	ds_bpermute_b32 v91, v1, v90
	s_cmp_eq_u32 s41, 0
	s_cselect_b64 s[4:5], -1, 0
	s_waitcnt lgkmcnt(7)
	v_mfma_f32_32x32x16_bf16 v[50:65], v[168:171], v[202:205], v[50:65]
	s_waitcnt lgkmcnt(5)
	v_mfma_f32_32x32x16_bf16 v[34:49], v[172:175], v[202:205], v[34:49]
	ds_read_b64_tr_b16 v[184:185], v248 offset:52224
	ds_read_b64_tr_b16 v[186:187], v248 offset:52736
	ds_read_b64_tr_b16 v[188:189], v248 offset:56320
	ds_read_b64_tr_b16 v[190:191], v248 offset:56832
	s_waitcnt lgkmcnt(7)
	v_mfma_f32_32x32x16_bf16 v[18:33], v[176:179], v[202:205], v[18:33]
	s_waitcnt lgkmcnt(5)
	v_mfma_f32_32x32x16_bf16 v[2:17], v[180:183], v[202:205], v[2:17]
	ds_read_b64_tr_b16 v[160:161], v248 offset:60416
	ds_read_b64_tr_b16 v[162:163], v248 offset:60928
	ds_read_b64_tr_b16 v[242:243], v248 offset:64512
	ds_read_b64_tr_b16 v[244:245], v248 offset:65024
	s_waitcnt lgkmcnt(6)
	v_mfma_f32_32x32x16_bf16 v[50:65], v[184:187], v[206:209], v[50:65]
	s_waitcnt lgkmcnt(4)
	v_mfma_f32_32x32x16_bf16 v[34:49], v[188:191], v[206:209], v[34:49]
	s_waitcnt lgkmcnt(2)
	v_mfma_f32_32x32x16_bf16 v[18:33], v[160:163], v[206:209], v[18:33]
	s_waitcnt lgkmcnt(0)
	v_mfma_f32_32x32x16_bf16 v[2:17], v[242:245], v[206:209], v[2:17]
	v_add_f32_e32 v90, v90, v91
	v_cndmask_b32_e64 v91, v148, 1.0, s[4:5]
	v_div_scale_f32 v92, s[22:23], v90, v90, v91
	v_rcp_f32_e32 v93, v92
	s_waitcnt vmcnt(0) lgkmcnt(0)
	s_barrier
	v_fma_f32 v74, -v92, v93, 1.0
	v_fmac_f32_e32 v93, v74, v93
	v_div_scale_f32 v74, vcc, v91, v90, v91
	v_mul_f32_e32 v75, v74, v93
	v_fma_f32 v76, -v92, v75, v74
	v_fmac_f32_e32 v75, v76, v93
	v_fma_f32 v66, -v92, v75, v74
	s_nop 0
	v_div_fmas_f32 v66, v66, v93, v75
	v_div_fixup_f32 v82, v66, v90, v91
	v_lshl_add_u32 v70, s27, 13, v150
	s_and_b64 vcc, exec, s[4:5]
	s_cbranch_vccnz .LBB0_991
	v_mul_f32_e32 v66, v50, v82
	v_mul_f32_e32 v67, v51, v82
	v_cvt_pk_f16_f32 v66, v66, v67
	v_mul_f32_e32 v67, v52, v82
	v_mul_f32_e32 v68, v53, v82
	v_cvt_pk_f16_f32 v67, v67, v68
	ds_write2st64_b32 v70, v66, v67 offset1:1
	v_mul_f32_e32 v66, v54, v82
	v_mul_f32_e32 v67, v55, v82
	v_cvt_pk_f16_f32 v66, v66, v67
	v_mul_f32_e32 v67, v56, v82
	v_mul_f32_e32 v68, v57, v82
	v_cvt_pk_f16_f32 v67, v67, v68
	ds_write2st64_b32 v70, v66, v67 offset0:2 offset1:3
	v_mul_f32_e32 v66, v58, v82
	v_mul_f32_e32 v67, v59, v82
	v_cvt_pk_f16_f32 v66, v66, v67
	v_mul_f32_e32 v67, v60, v82
	v_mul_f32_e32 v68, v61, v82
	v_cvt_pk_f16_f32 v67, v67, v68
	ds_write2st64_b32 v70, v66, v67 offset0:4 offset1:5
	v_mul_f32_e32 v66, v62, v82
	v_mul_f32_e32 v67, v63, v82
	v_cvt_pk_f16_f32 v66, v66, v67
	v_mul_f32_e32 v67, v64, v82
	v_mul_f32_e32 v68, v65, v82
	v_cvt_pk_f16_f32 v67, v67, v68
	ds_write2st64_b32 v70, v66, v67 offset0:6 offset1:7
	v_mul_f32_e32 v66, v34, v82
	v_mul_f32_e32 v67, v35, v82
	v_cvt_pk_f16_f32 v66, v66, v67
	v_mul_f32_e32 v67, v36, v82
	v_mul_f32_e32 v68, v37, v82
	v_cvt_pk_f16_f32 v67, v67, v68
	ds_write2st64_b32 v70, v66, v67 offset0:8 offset1:9
	v_mul_f32_e32 v66, v38, v82
	v_mul_f32_e32 v67, v39, v82
	v_cvt_pk_f16_f32 v66, v66, v67
	v_mul_f32_e32 v67, v40, v82
	v_mul_f32_e32 v68, v41, v82
	v_cvt_pk_f16_f32 v67, v67, v68
	ds_write2st64_b32 v70, v66, v67 offset0:10 offset1:11
	v_mul_f32_e32 v66, v42, v82
	v_mul_f32_e32 v67, v43, v82
	v_cvt_pk_f16_f32 v66, v66, v67
	v_mul_f32_e32 v67, v44, v82
	v_mul_f32_e32 v68, v45, v82
	v_cvt_pk_f16_f32 v67, v67, v68
	ds_write2st64_b32 v70, v66, v67 offset0:12 offset1:13
	v_mul_f32_e32 v66, v46, v82
	v_mul_f32_e32 v67, v47, v82
	v_cvt_pk_f16_f32 v66, v66, v67
	v_mul_f32_e32 v67, v48, v82
	v_mul_f32_e32 v68, v49, v82
	v_cvt_pk_f16_f32 v67, v67, v68
	ds_write2st64_b32 v70, v66, v67 offset0:14 offset1:15
	v_mul_f32_e32 v66, v18, v82
	v_mul_f32_e32 v67, v19, v82
	v_cvt_pk_f16_f32 v66, v66, v67
	v_mul_f32_e32 v67, v20, v82
	v_mul_f32_e32 v68, v21, v82
	v_cvt_pk_f16_f32 v67, v67, v68
	ds_write2st64_b32 v70, v66, v67 offset0:16 offset1:17
	v_mul_f32_e32 v66, v22, v82
	v_mul_f32_e32 v67, v23, v82
	v_cvt_pk_f16_f32 v66, v66, v67
	v_mul_f32_e32 v67, v24, v82
	v_mul_f32_e32 v68, v25, v82
	v_cvt_pk_f16_f32 v67, v67, v68
	ds_write2st64_b32 v70, v66, v67 offset0:18 offset1:19
	v_mul_f32_e32 v66, v26, v82
	v_mul_f32_e32 v67, v27, v82
	v_cvt_pk_f16_f32 v66, v66, v67
	v_mul_f32_e32 v67, v28, v82
	v_mul_f32_e32 v68, v29, v82
	v_cvt_pk_f16_f32 v67, v67, v68
	ds_write2st64_b32 v70, v66, v67 offset0:20 offset1:21
	v_mul_f32_e32 v66, v30, v82
	v_mul_f32_e32 v67, v31, v82
	v_cvt_pk_f16_f32 v66, v66, v67
	v_mul_f32_e32 v67, v32, v82
	v_mul_f32_e32 v68, v33, v82
	v_cvt_pk_f16_f32 v67, v67, v68
	ds_write2st64_b32 v70, v66, v67 offset0:22 offset1:23
	v_mul_f32_e32 v66, v2, v82
	v_mul_f32_e32 v67, v3, v82
	v_cvt_pk_f16_f32 v66, v66, v67
	v_mul_f32_e32 v67, v4, v82
	v_mul_f32_e32 v68, v5, v82
	v_cvt_pk_f16_f32 v67, v67, v68
	ds_write2st64_b32 v70, v66, v67 offset0:24 offset1:25
	v_mul_f32_e32 v66, v6, v82
	v_mul_f32_e32 v67, v7, v82
	v_cvt_pk_f16_f32 v66, v66, v67
	v_mul_f32_e32 v67, v8, v82
	v_mul_f32_e32 v68, v9, v82
	v_cvt_pk_f16_f32 v67, v67, v68
	ds_write2st64_b32 v70, v66, v67 offset0:26 offset1:27
	v_mul_f32_e32 v66, v10, v82
	v_mul_f32_e32 v67, v11, v82
	v_cvt_pk_f16_f32 v66, v66, v67
	v_mul_f32_e32 v67, v12, v82
	v_mul_f32_e32 v68, v13, v82
	v_cvt_pk_f16_f32 v67, v67, v68
	ds_write2st64_b32 v70, v66, v67 offset0:28 offset1:29
	v_mul_f32_e32 v66, v14, v82
	v_mul_f32_e32 v67, v15, v82
	v_cvt_pk_f16_f32 v66, v66, v67
	v_mul_f32_e32 v67, v16, v82
	v_mul_f32_e32 v68, v17, v82
	v_cvt_pk_f16_f32 v67, v67, v68
	ds_write2st64_b32 v70, v66, v67 offset0:30 offset1:31
